# K/V cache conversion (prologue_b): the four item loops start at rotated wave offsets so every wave gets 9-10 items instead of 12 for waves 0..255 and 8 for the rest
# speedup vs baseline: 1.0095x; 1.0095x over previous
; DI void kc_item(const float* src, int past, int nh, int band, int krows, bf16_t* KF, int item, int lane) {
;     const int nrb = past / 32, h = item % nh, rb = (item / nh) % nrb, b = item / (nh * nrb), r = lane & 31, hh = lane >> 5;
;     const float* sp = src + (((size_t)b * past + rb * 32 + r) * nh + h) * 64 + 8 * hh;
;     bf16_t* d = KF + (((size_t)h * (krows >> 5) + ((SEQ + b * band) >> 5) + rb) * 4 * 64 + lane) * 8;
; #pragma unroll
; DI void prologue_b(KArgs ap, int gw, int NGW, int lane) {
;     ...
;     for (int it = gw; it < NSTREAM * 16 * 8; it += NGW) kc_item(cak, 512, 8, 576, KA_ROWS, (bf16_t*)(ws + WS_KA), it, lane);
;     for (int it = gw; it < NSTREAM * 4 * 2; it += NGW) kc_item(cbk, 128, 2, 192, KB_ROWS, (bf16_t*)(ws + WS_KB), it, lane);
.LBB0_538:
	s_add_i32 s16, s16, 0x100
	s_sub_i32 vcc_lo, s16, s17
	s_cmp_ge_i32 s16, s17
	s_cselect_b32 s16, vcc_lo, s16
	s_cmpk_lt_i32 s16, 0x100
	s_cselect_b64 s[10:11], -1, 0
	s_cmpk_gt_i32 s16, 0xff
	s_cbranch_scc1 .LBB0_541
	v_mov_b32_e32 v5, 0
	v_lshlrev_b32_e32 v4, 2, v1
	s_waitcnt lgkmcnt(0)
	v_lshl_add_u64 v[2:3], s[6:7], 0, v[4:5]
	v_lshlrev_b32_e32 v4, 4, v190
	v_lshl_add_u64 v[4:5], s[0:1], 0, v[4:5]
	s_mov_b64 s[6:7], 0x8400000
	v_and_b32_e32 v0, 31, v226
	v_lshl_add_u64 v[4:5], v[4:5], 0, s[6:7]
	s_mov_b32 s6, s16

; DI void vt_item(const float* src, int past, int nh, int band, int krows, bf16_t* VT, int item, int lane) {
;     const int nrb = past / 32, rb = item % nrb, h = (item / nrb) % nh, b = item / (nrb * nh), r0 = rb * 32;
;     float v[32];
; #pragma unroll
;     for (int i = 0; i < 32; ++i) v[i] = src[(((size_t)b * past + r0 + i) * nh + h) * 64 + lane];
;     const int krow = SEQ + b * band + r0;
; DI void prologue_b(KArgs ap, int gw, int NGW, int lane) {
;     ...
;     for (int it = gw; it < NSTREAM * 4 * 2; it += NGW) kc_item(cbk, 128, 2, 192, KB_ROWS, (bf16_t*)(ws + WS_KB), it, lane);
;     for (int it = gw; it < NSTREAM * 8 * 16; it += NGW) vt_item(cav, 512, 8, 576, KA_ROWS, (bf16_t*)(ws + WS_VTA), it, lane);
.LBB0_541:
	s_add_i32 s16, s16, 0x100
	s_sub_i32 vcc_lo, s16, s17
	s_cmp_ge_i32 s16, s17
	s_cselect_b32 s16, vcc_lo, s16
	s_andn2_b64 vcc, exec, s[12:13]
	v_lshlrev_b32_e32 v0, 2, v190
	s_cbranch_vccnz .LBB0_544
	v_mov_b32_e32 v1, 0
	s_waitcnt lgkmcnt(0)
	v_lshl_add_u64 v[2:3], s[4:5], 0, v[0:1]
	v_and_b32_e32 v4, 31, v226
	s_movk_i32 s4, 0x80
	v_and_or_b32 v4, v145, s4, v4
	v_lshlrev_b32_e32 v4, 4, v4
	v_mov_b32_e32 v5, v1
	v_lshl_add_u64 v[4:5], s[0:1], 0, v[4:5]
	s_mov_b64 s[4:5], 0x6200000
	v_lshl_add_u64 v[4:5], v[4:5], 0, s[4:5]
	s_lshl_b32 s12, s16, 5
	s_lshl_b32 s13, s17, 5
	s_movk_i32 s18, 0x1000
	s_movk_i32 s19, 0x2000
	s_movk_i32 s20, 0x3000
	s_movk_i32 s21, 0x4000
	s_movk_i32 s22, 0x5000
	s_movk_i32 s23, 0x6000
	s_movk_i32 s24, 0x7000
	s_mov_b32 s25, 0x8000
	s_mov_b32 s26, 0x9000
	s_mov_b32 s27, 0xa000
	s_mov_b32 s28, 0xb000
	s_mov_b32 s29, 0xc000
	s_mov_b32 s30, 0xd000
	s_mov_b32 s31, 0xe000
	s_mov_b32 s33, 0xf000
	s_mov_b32 s34, s16

; DI void vt_item(const float* src, int past, int nh, int band, int krows, bf16_t* VT, int item, int lane) {
;     const int nrb = past / 32, rb = item % nrb, h = (item / nrb) % nh, b = item / (nrb * nh), r0 = rb * 32;
;     float v[32];
; #pragma unroll
;     for (int i = 0; i < 32; ++i) v[i] = src[(((size_t)b * past + r0 + i) * nh + h) * 64 + lane];
;     const int krow = SEQ + b * band + r0;
; DI void prologue_b(KArgs ap, int gw, int NGW, int lane) {
;     ...
;     for (int it = gw; it < NSTREAM * 8 * 16; it += NGW) vt_item(cav, 512, 8, 576, KA_ROWS, (bf16_t*)(ws + WS_VTA), it, lane);
;     for (int it = gw; it < NSTREAM * 2 * 4; it += NGW) vt_item(cbv, 128, 2, 192, KB_ROWS, (bf16_t*)(ws + WS_VTB), it, lane);
.LBB0_544:
	s_add_i32 s16, s16, 0xc0
	s_sub_i32 vcc_lo, s16, s17
	s_cmp_ge_i32 s16, s17
	s_cselect_b32 s16, vcc_lo, s16
	s_cmpk_lt_i32 s16, 0x100
	s_cselect_b64 s[10:11], -1, 0
	s_andn2_b64 vcc, exec, s[10:11]
	s_cbranch_vccnz .LBB0_547
	v_mov_b32_e32 v1, 0
	s_waitcnt lgkmcnt(0)
	v_lshl_add_u64 v[2:3], s[8:9], 0, v[0:1]
	v_and_b32_e32 v0, 31, v226
	s_movk_i32 s4, 0x80
	v_and_or_b32 v0, v145, s4, v0
	v_lshlrev_b32_e32 v0, 4, v0
	v_lshl_add_u64 v[0:1], s[0:1], 0, v[0:1]
	s_mov_b64 s[0:1], 0x8a00000
	v_lshl_add_u64 v[0:1], v[0:1], 0, s[0:1]
	s_lshl_b32 s0, s16, 5
	s_lshl_b32 s1, s17, 5
	s_movk_i32 s4, 0x1000
	s_movk_i32 s5, 0x2000
	s_movk_i32 s6, 0x3000
